# SSD: the scan's two dt loads are issued right after the chunk-start barrier (fly during tile staging) instead of inside the scan
# baseline (speedup 1.0000x reference)
.LBB0_1078:
	s_sub_i32 s3, 15, s2
	v_cvt_pk_bf16_f32 v2, v92, v93
	v_cvt_pk_bf16_f32 v3, v94, v95
	s_and_b64 s[0:1], s[4:5], exec
	s_barrier
	s_cselect_b32 s90, s2, s3
	v_readlane_b32 s92, v254, 25
	v_readlane_b32 s93, v254, 26
	s_mul_i32 s91, s90, 0x80
	v_mov_b32_e32 v249, 0
	v_or_b32_e32 v248, s91, v156
	s_nop 1
	v_lshl_add_u64 v[248:249], v[248:249], 2, s[92:93]
	global_load_dword v250, v[248:249], off
	global_load_dword v251, v[248:249], off offset:256
	s_waitcnt vmcnt(13)
	ds_write_b128 v165, v[4:7] offset:17408
	s_waitcnt vmcnt(12)
	ds_write_b128 v166, v[8:11]
	s_waitcnt vmcnt(11)
	ds_write_b128 v165, v[12:15] offset:52224
	s_waitcnt vmcnt(10)
	ds_write_b128 v165, v[16:19] offset:26112
	s_waitcnt vmcnt(9)
	ds_write_b128 v168, v[20:23]
	s_waitcnt vmcnt(8)
	ds_write_b128 v165, v[24:27] offset:60928
	s_waitcnt vmcnt(7)
	ds_write_b128 v165, v[28:31] offset:34816
	s_waitcnt vmcnt(6)
	ds_write_b128 v166, v[32:35] offset:17408
	s_waitcnt vmcnt(5)
	ds_write_b128 v167, v[36:39] offset:17408
	s_waitcnt vmcnt(3)
	ds_write_b128 v165, v[40:43] offset:43520
	s_waitcnt vmcnt(2)
	ds_write_b128 v166, v[44:47] offset:26112
	s_waitcnt vmcnt(4)
	ds_write_b128 v167, v[48:51] offset:26112
	s_waitcnt vmcnt(3)
	ds_write_b128 v208, v[52:55]
	s_waitcnt vmcnt(2)
	ds_write_b128 v208, v[56:59] offset:8704
	ds_write_b64 v222, v[2:3]
	v_cvt_pk_bf16_f32 v2, v96, v97
	v_cvt_pk_bf16_f32 v3, v98, v99
	v_readlane_b32 s6, v254, 44
	s_cselect_b32 s0, s2, s3
	ds_write_b64 v222, v[2:3] offset:4352
	v_cvt_pk_bf16_f32 v2, v100, v101
	v_cvt_pk_bf16_f32 v3, v102, v103
	v_readlane_b32 s7, v254, 45
	s_lshl_b32 s3, s0, 7
	ds_write_b64 v222, v[2:3] offset:8704
	v_cvt_pk_bf16_f32 v2, v104, v105
	v_cvt_pk_bf16_f32 v3, v106, v107
	s_andn2_b64 vcc, exec, s[6:7]
	ds_write_b64 v222, v[2:3] offset:13056
	s_waitcnt vmcnt(0)
	s_cbranch_vccnz .LBB0_1082
	v_readlane_b32 s6, v254, 25
	s_nop 0
	v_readlane_b32 s7, v254, 26
	v_and_b32_e32 v54, 64, v209
	s_mov_b32 s1, 1
	s_nop 0
	v_mov_b32_e32 v0, v250
	v_mov_b32_e32 v2, v251
	s_nop 0
	s_waitcnt vmcnt(1)
	v_mul_f32_e64 v53, v0, -v212
	s_waitcnt vmcnt(0)
	v_mul_f32_e64 v52, v2, -v212
	v_mov_b32_e32 v3, v53
	v_mov_b32_e32 v55, v52
